# ph4 up-projection outputs (Q, KV) written with nontemporal stores like the other streamed GEMM outputs
# speedup vs baseline: 1.0031x; 1.0031x over previous
; DI unsigned pk2(float a, float b) { f32x2 v = {a, b}; bf2_t r = __builtin_convertvector(v, bf2_t); return __builtin_bit_cast(unsigned, r); }
; DI f32x16 mfma32(bf16x8 a, bf16x8 b, f32x16 c) { return __builtin_amdgcn_mfma_f32_32x32x16_bf16(a, b, c, 0, 0, 0); }
;     ...
;       acc[0][0] = mfma32(bfr[kk][0], af[kk][0], acc[0][0]); acc[0][1] = mfma32(bfr[kk][1], af[kk][0], acc[0][1]);
;       acc[1][0] = mfma32(bfr[kk][0], af[kk][1], acc[1][0]); acc[1][1] = mfma32(bfr[kk][1], af[kk][1], acc[1][1]);
;       acc[0][2] = mfma32(bfr[kk][2], af[kk][0], acc[0][2]); acc[0][3] = mfma32(bfr[kk][3], af[kk][0], acc[0][3]);
;       acc[1][2] = mfma32(bfr[kk][2], af[kk][1], acc[1][2]); acc[1][3] = mfma32(bfr[kk][3], af[kk][1], acc[1][3]);
;     }
;     __builtin_amdgcn_sched_group_barrier(0x100, 12, 0);
;     __builtin_amdgcn_sched_group_barrier(0x010, 6, 0);
;     __builtin_amdgcn_sched_group_barrier(0x008, 16, 0);
;     asm volatile("s_waitcnt vmcnt(6) lgkmcnt(0)" ::: "memory");
;     __builtin_amdgcn_s_barrier();
;     asm volatile("" ::: "memory");
;     s0 = (s0 == 2 * STG) ? 0 : s0 + STG;
;     s2 = (s2 == 2 * STG) ? 0 : s2 + STG;
;   }
;   asm volatile("s_waitcnt vmcnt(0)" ::: "memory");
;   __builtin_amdgcn_s_barrier();
;   asm volatile("" ::: "memory");
;     ...
;   {
;     const int h = lane >> 5, cl = lane & 31;
; #pragma unroll
;     for (int i = 0; i < 2; ++i)
; #pragma unroll
;       for (int j = 0; j < 4; ++j)
; #pragma unroll
;         for (int g = 0; g < 4; ++g) {
;           u32x2 w; w.x = pk2(acc[i][j][4 * g], acc[i][j][4 * g + 1]); w.y = pk2(acc[i][j][4 * g + 2], acc[i][j][4 * g + 3]);
;           *(u32x2*)(smem + (wr * 64 + i * 32 + cl) * 528 + (wc * 128 + j * 32 + 8 * g + 4 * h) * 2) = w;
;         }
;   }
.LBB0_148:
	ds_read_b128 v[138:141], v228 offset:0
	ds_read_b128 v[162:165], v229 offset:8192
	ds_read_b128 v[166:169], v229 offset:10240
	ds_read_b128 v[142:145], v228 offset:2048
	ds_read_b128 v[146:149], v229 offset:12288
	ds_read_b128 v[150:153], v229 offset:14336
	s_waitcnt lgkmcnt(6)
	v_mfma_f32_32x32x16_bf16 v[114:129], v[182:185], v[154:157], v[114:129]
	v_mfma_f32_32x32x16_bf16 v[98:113], v[178:181], v[154:157], v[98:113]
	v_mfma_f32_32x32x16_bf16 v[66:81], v[182:185], v[158:161], v[66:81]
	v_mfma_f32_32x32x16_bf16 v[34:49], v[178:181], v[158:161], v[34:49]
	v_mfma_f32_32x32x16_bf16 v[82:97], v[174:177], v[154:157], v[82:97]
	v_mfma_f32_32x32x16_bf16 v[50:65], v[170:173], v[154:157], v[50:65]
	v_mfma_f32_32x32x16_bf16 v[18:33], v[174:177], v[158:161], v[18:33]
	v_mfma_f32_32x32x16_bf16 v[2:17], v[170:173], v[158:161], v[2:17]
	s_waitcnt vmcnt(0) lgkmcnt(0)
	s_barrier
	ds_read_b128 v[154:157], v226 offset:24576
	ds_read_b128 v[182:185], v227 offset:32768
	ds_read_b128 v[178:181], v227 offset:34816
	ds_read_b128 v[158:161], v226 offset:26624
	ds_read_b128 v[174:177], v227 offset:36864
	ds_read_b128 v[170:173], v227 offset:38912
	v_mfma_f32_32x32x16_bf16 v[114:129], v[162:165], v[138:141], v[114:129]
	v_mfma_f32_32x32x16_bf16 v[98:113], v[166:169], v[138:141], v[98:113]
	v_mfma_f32_32x32x16_bf16 v[66:81], v[162:165], v[142:145], v[66:81]
	v_mfma_f32_32x32x16_bf16 v[34:49], v[166:169], v[142:145], v[34:49]
	v_mfma_f32_32x32x16_bf16 v[82:97], v[146:149], v[138:141], v[82:97]
	v_mfma_f32_32x32x16_bf16 v[50:65], v[150:153], v[138:141], v[50:65]
	v_mfma_f32_32x32x16_bf16 v[18:33], v[146:149], v[142:145], v[18:33]
	v_mfma_f32_32x32x16_bf16 v[2:17], v[150:153], v[142:145], v[2:17]
	ds_read_b128 v[138:141], v228 offset:24576
	ds_read_b128 v[162:165], v229 offset:32768
	ds_read_b128 v[166:169], v229 offset:34816
	ds_read_b128 v[142:145], v228 offset:26624
	ds_read_b128 v[146:149], v229 offset:36864
	ds_read_b128 v[150:153], v229 offset:38912
	s_waitcnt lgkmcnt(6)
	v_mfma_f32_32x32x16_bf16 v[114:129], v[182:185], v[154:157], v[114:129]
	v_mfma_f32_32x32x16_bf16 v[98:113], v[178:181], v[154:157], v[98:113]
	v_mfma_f32_32x32x16_bf16 v[66:81], v[182:185], v[158:161], v[66:81]
	v_mfma_f32_32x32x16_bf16 v[34:49], v[178:181], v[158:161], v[34:49]
	v_mfma_f32_32x32x16_bf16 v[82:97], v[174:177], v[154:157], v[82:97]
	v_mfma_f32_32x32x16_bf16 v[50:65], v[170:173], v[154:157], v[50:65]
	v_mfma_f32_32x32x16_bf16 v[18:33], v[174:177], v[158:161], v[18:33]
	v_mfma_f32_32x32x16_bf16 v[2:17], v[170:173], v[158:161], v[2:17]
	s_waitcnt lgkmcnt(0)
	v_mfma_f32_32x32x16_bf16 v[114:129], v[162:165], v[138:141], v[114:129]
	v_mfma_f32_32x32x16_bf16 v[98:113], v[166:169], v[138:141], v[98:113]
	v_mfma_f32_32x32x16_bf16 v[66:81], v[162:165], v[142:145], v[66:81]
	v_mfma_f32_32x32x16_bf16 v[34:49], v[166:169], v[142:145], v[34:49]
	v_mfma_f32_32x32x16_bf16 v[82:97], v[146:149], v[138:141], v[82:97]
	v_mfma_f32_32x32x16_bf16 v[50:65], v[150:153], v[138:141], v[50:65]
	v_mfma_f32_32x32x16_bf16 v[18:33], v[146:149], v[142:145], v[18:33]
	v_mfma_f32_32x32x16_bf16 v[2:17], v[150:153], v[142:145], v[2:17]
	s_waitcnt lgkmcnt(0)
	s_mov_b32 s101, 0
	s_mov_b32 s71, 0
	s_setprio 0
	v_mul_lo_u32 v0, v197, s55
	v_add_u32_e32 v0, 16, v0
	s_nop 1
	v_cvt_pk_bf16_f32 v114, v114, v115
	v_cvt_pk_bf16_f32 v115, v116, v117
	v_lshlrev_b32_e32 v116, 3, v196
	s_lshl_b32 s10, s42, 1
	v_add3_u32 v0, v0, v116, s10
	v_cvt_pk_bf16_f32 v116, v118, v119
	v_cvt_pk_bf16_f32 v117, v120, v121
	v_cvt_pk_bf16_f32 v98, v98, v99
	v_cvt_pk_bf16_f32 v99, v100, v101
	v_cvt_pk_bf16_f32 v100, v102, v103
	v_cvt_pk_bf16_f32 v101, v104, v105
	v_cvt_pk_bf16_f32 v82, v82, v83
	v_cvt_pk_bf16_f32 v83, v84, v85
	v_cvt_pk_bf16_f32 v84, v86, v87
	v_cvt_pk_bf16_f32 v85, v88, v89
	v_cvt_pk_bf16_f32 v50, v50, v51
	v_cvt_pk_bf16_f32 v51, v52, v53
	v_cvt_pk_bf16_f32 v52, v54, v55
	v_cvt_pk_bf16_f32 v53, v56, v57
	s_waitcnt vmcnt(0)
	s_barrier
	ds_write2_b64 v0, v[114:115], v[116:117] offset1:2
	v_cvt_pk_bf16_f32 v114, v122, v123
	v_cvt_pk_bf16_f32 v115, v124, v125
	v_cvt_pk_bf16_f32 v116, v126, v127
	v_cvt_pk_bf16_f32 v117, v128, v129
	ds_write2_b64 v0, v[98:99], v[100:101] offset0:8 offset1:10
	v_cvt_pk_bf16_f32 v98, v106, v107
	v_cvt_pk_bf16_f32 v99, v108, v109
	v_cvt_pk_bf16_f32 v100, v110, v111
	v_cvt_pk_bf16_f32 v101, v112, v113
	ds_write2_b64 v0, v[82:83], v[84:85] offset0:16 offset1:18
	v_cvt_pk_bf16_f32 v82, v90, v91
	v_cvt_pk_bf16_f32 v83, v92, v93
	v_cvt_pk_bf16_f32 v84, v94, v95
	v_cvt_pk_bf16_f32 v85, v96, v97
	ds_write2_b64 v0, v[50:51], v[52:53] offset0:24 offset1:26
	v_cvt_pk_bf16_f32 v50, v58, v59
	v_cvt_pk_bf16_f32 v51, v60, v61
	v_cvt_pk_bf16_f32 v52, v62, v63
	v_cvt_pk_bf16_f32 v53, v64, v65
	ds_write2_b64 v0, v[114:115], v[116:117] offset0:4 offset1:6
	ds_write2_b64 v0, v[98:99], v[100:101] offset0:12 offset1:14
	ds_write2_b64 v0, v[82:83], v[84:85] offset0:20 offset1:22
	ds_write2_b64 v0, v[50:51], v[52:53] offset0:28 offset1:30
	v_cvt_pk_bf16_f32 v50, v66, v67
	v_cvt_pk_bf16_f32 v51, v68, v69
	v_cvt_pk_bf16_f32 v52, v70, v71
	v_cvt_pk_bf16_f32 v53, v72, v73
	v_add_u32_e32 v0, 0x4000, v0
	v_cvt_pk_bf16_f32 v34, v34, v35
	v_cvt_pk_bf16_f32 v35, v36, v37
	v_cvt_pk_bf16_f32 v36, v38, v39
	v_cvt_pk_bf16_f32 v37, v40, v41
	v_cvt_pk_bf16_f32 v18, v18, v19
	v_cvt_pk_bf16_f32 v19, v20, v21
	v_cvt_pk_bf16_f32 v20, v22, v23
	v_cvt_pk_bf16_f32 v21, v24, v25
	v_cvt_pk_bf16_f32 v2, v2, v3
	v_cvt_pk_bf16_f32 v3, v4, v5
	v_cvt_pk_bf16_f32 v4, v6, v7
	v_cvt_pk_bf16_f32 v5, v8, v9
	ds_write2_b64 v0, v[50:51], v[52:53] offset0:64 offset1:66
	v_cvt_pk_bf16_f32 v50, v74, v75
	v_cvt_pk_bf16_f32 v51, v76, v77
	v_cvt_pk_bf16_f32 v52, v78, v79
	v_cvt_pk_bf16_f32 v53, v80, v81
	ds_write2_b64 v0, v[34:35], v[36:37] offset0:72 offset1:74
	v_cvt_pk_bf16_f32 v34, v42, v43
	v_cvt_pk_bf16_f32 v35, v44, v45
	v_cvt_pk_bf16_f32 v36, v46, v47
	v_cvt_pk_bf16_f32 v37, v48, v49
	ds_write2_b64 v0, v[18:19], v[20:21] offset0:80 offset1:82
	v_cvt_pk_bf16_f32 v18, v26, v27
	v_cvt_pk_bf16_f32 v19, v28, v29
	v_cvt_pk_bf16_f32 v20, v30, v31
	v_cvt_pk_bf16_f32 v21, v32, v33
	ds_write2_b64 v0, v[2:3], v[4:5] offset0:88 offset1:90
	v_cvt_pk_bf16_f32 v2, v10, v11
	v_cvt_pk_bf16_f32 v3, v12, v13
	v_cvt_pk_bf16_f32 v4, v14, v15
	v_cvt_pk_bf16_f32 v5, v16, v17
	s_lshl_b64 s[12:13], s[12:13], 1
	ds_write2_b64 v0, v[50:51], v[52:53] offset0:68 offset1:70
	ds_write2_b64 v0, v[34:35], v[36:37] offset0:76 offset1:78
	ds_write2_b64 v0, v[18:19], v[20:21] offset0:84 offset1:86
	ds_write2_b64 v0, v[2:3], v[4:5] offset0:92 offset1:94
	s_waitcnt vmcnt(0) lgkmcnt(0)
	s_barrier
; #define GAS __attribute__((address_space(1)))
;     ...
;   int tid2 = tid; asm volatile("" : "+v"(tid2));
;   if (EPI == 0) {
; #pragma unroll
;     for (int i = 0; i < 16; ++i) {
;       const int id = tid2 + 256 * i, r = id >> 5, c8 = (id & 31) * 8;
;       const u32x4 v = *(const u32x4*)(smem + r * 528 + c8 * 2);
;       *(GAS u32x4*)(ea.out + (size_t)(m0 + r) * ea.ldo + n0 + c8) = v;
;     }
	s_add_u32 s12, s16, s12
	v_lshlrev_b32_e32 v0, 4, v189
	v_and_b32_e32 v0, 0x1f0, v0
	s_addc_u32 s13, s17, s13
	v_add_u32_e32 v10, 16, v0
	v_lshl_add_u64 v[12:13], s[12:13], 0, v[0:1]
	v_ashrrev_i32_e32 v0, 5, v189
	v_mad_u64_u32 v[2:3], s[12:13], v0, s55, v[10:11]
	ds_read_b128 v[2:5], v2
	v_add_u32_e32 v6, s41, v0
	v_ashrrev_i32_e32 v7, 31, v6
	v_add_u32_e32 v0, 0x100, v189
	v_lshlrev_b64 v[6:7], 11, v[6:7]
	v_ashrrev_i32_e32 v0, 5, v0
	v_lshl_add_u64 v[14:15], v[12:13], 0, v[6:7]
	v_mad_u64_u32 v[6:7], s[12:13], v0, s55, v[10:11]
	ds_read_b128 v[6:9], v6
	s_waitcnt lgkmcnt(1)
	global_store_dwordx4 v[14:15], v[2:5], off nt
	v_readlane_b32 s44, v250, 17
	s_nop 0
	v_add_u32_e32 v2, s41, v0
	v_ashrrev_i32_e32 v3, 31, v2
	v_lshlrev_b64 v[2:3], 11, v[2:3]
	v_add_u32_e32 v0, 0x200, v189
	v_lshl_add_u64 v[2:3], v[12:13], 0, v[2:3]
	v_ashrrev_i32_e32 v0, 5, v0
	s_waitcnt lgkmcnt(0)
	global_store_dwordx4 v[2:3], v[6:9], off nt
	v_mad_u64_u32 v[2:3], s[12:13], v0, s55, v[10:11]
	ds_read_b128 v[2:5], v2
	v_add_u32_e32 v6, s41, v0
	v_ashrrev_i32_e32 v7, 31, v6
	v_add_u32_e32 v0, 0x300, v189
	v_lshlrev_b64 v[6:7], 11, v[6:7]
	v_ashrrev_i32_e32 v0, 5, v0
	v_lshl_add_u64 v[14:15], v[12:13], 0, v[6:7]
	v_mad_u64_u32 v[6:7], s[12:13], v0, s55, v[10:11]
	ds_read_b128 v[6:9], v6
	s_waitcnt lgkmcnt(1)
	global_store_dwordx4 v[14:15], v[2:5], off nt
	s_nop 1
	v_add_u32_e32 v2, s41, v0
	v_ashrrev_i32_e32 v3, 31, v2
	v_lshlrev_b64 v[2:3], 11, v[2:3]
	v_add_u32_e32 v0, 0x400, v189
	v_lshl_add_u64 v[2:3], v[12:13], 0, v[2:3]
	v_ashrrev_i32_e32 v0, 5, v0
	s_waitcnt lgkmcnt(0)
	global_store_dwordx4 v[2:3], v[6:9], off nt
	v_mad_u64_u32 v[2:3], s[12:13], v0, s55, v[10:11]
	ds_read_b128 v[2:5], v2
	v_add_u32_e32 v6, s41, v0
	v_ashrrev_i32_e32 v7, 31, v6
	v_add_u32_e32 v0, 0x500, v189
	v_lshlrev_b64 v[6:7], 11, v[6:7]
	v_ashrrev_i32_e32 v0, 5, v0
	v_lshl_add_u64 v[14:15], v[12:13], 0, v[6:7]
	v_mad_u64_u32 v[6:7], s[12:13], v0, s55, v[10:11]
	ds_read_b128 v[6:9], v6
	s_waitcnt lgkmcnt(1)
	global_store_dwordx4 v[14:15], v[2:5], off nt
	s_nop 1
	v_add_u32_e32 v2, s41, v0
	v_ashrrev_i32_e32 v3, 31, v2
	v_lshlrev_b64 v[2:3], 11, v[2:3]
	v_add_u32_e32 v0, 0x600, v189
	v_lshl_add_u64 v[2:3], v[12:13], 0, v[2:3]
	v_ashrrev_i32_e32 v0, 5, v0
	s_waitcnt lgkmcnt(0)
	global_store_dwordx4 v[2:3], v[6:9], off nt
	v_mad_u64_u32 v[2:3], s[12:13], v0, s55, v[10:11]
	ds_read_b128 v[2:5], v2
	v_add_u32_e32 v6, s41, v0
	v_ashrrev_i32_e32 v7, 31, v6
	v_add_u32_e32 v0, 0x700, v189
	v_lshlrev_b64 v[6:7], 11, v[6:7]
	v_ashrrev_i32_e32 v0, 5, v0
	v_lshl_add_u64 v[14:15], v[12:13], 0, v[6:7]
	v_mad_u64_u32 v[6:7], s[12:13], v0, s55, v[10:11]
	ds_read_b128 v[6:9], v6
	s_waitcnt lgkmcnt(1)
	global_store_dwordx4 v[14:15], v[2:5], off nt
	s_nop 1
	v_add_u32_e32 v2, s41, v0
	v_ashrrev_i32_e32 v3, 31, v2
	v_lshlrev_b64 v[2:3], 11, v[2:3]
	v_add_u32_e32 v0, 0x800, v189
	v_lshl_add_u64 v[2:3], v[12:13], 0, v[2:3]
	v_ashrrev_i32_e32 v0, 5, v0
	s_waitcnt lgkmcnt(0)
	global_store_dwordx4 v[2:3], v[6:9], off nt
	v_mad_u64_u32 v[2:3], s[12:13], v0, s55, v[10:11]
	ds_read_b128 v[2:5], v2
	v_add_u32_e32 v6, s41, v0
	v_ashrrev_i32_e32 v7, 31, v6
	v_add_u32_e32 v0, 0x900, v189
	v_lshlrev_b64 v[6:7], 11, v[6:7]
	v_ashrrev_i32_e32 v0, 5, v0
	v_lshl_add_u64 v[14:15], v[12:13], 0, v[6:7]
	v_mad_u64_u32 v[6:7], s[12:13], v0, s55, v[10:11]
	ds_read_b128 v[6:9], v6
	s_waitcnt lgkmcnt(1)
	global_store_dwordx4 v[14:15], v[2:5], off nt
	s_nop 1
	v_add_u32_e32 v2, s41, v0
	v_ashrrev_i32_e32 v3, 31, v2
	v_lshlrev_b64 v[2:3], 11, v[2:3]
	v_add_u32_e32 v0, 0xa00, v189
	v_lshl_add_u64 v[2:3], v[12:13], 0, v[2:3]
	v_ashrrev_i32_e32 v0, 5, v0
	s_waitcnt lgkmcnt(0)
	global_store_dwordx4 v[2:3], v[6:9], off nt
	v_mad_u64_u32 v[2:3], s[12:13], v0, s55, v[10:11]
	ds_read_b128 v[2:5], v2
	v_add_u32_e32 v6, s41, v0
	v_ashrrev_i32_e32 v7, 31, v6
	v_add_u32_e32 v0, 0xb00, v189
	v_lshlrev_b64 v[6:7], 11, v[6:7]
	v_ashrrev_i32_e32 v0, 5, v0
	v_lshl_add_u64 v[14:15], v[12:13], 0, v[6:7]
	v_mad_u64_u32 v[6:7], s[12:13], v0, s55, v[10:11]
	ds_read_b128 v[6:9], v6
	s_waitcnt lgkmcnt(1)
	global_store_dwordx4 v[14:15], v[2:5], off nt
	s_nop 1
	v_add_u32_e32 v2, s41, v0
	v_ashrrev_i32_e32 v3, 31, v2
	v_lshlrev_b64 v[2:3], 11, v[2:3]
	v_add_u32_e32 v0, 0xc00, v189
	v_lshl_add_u64 v[2:3], v[12:13], 0, v[2:3]
	v_ashrrev_i32_e32 v0, 5, v0
	s_waitcnt lgkmcnt(0)
	global_store_dwordx4 v[2:3], v[6:9], off nt
	v_mad_u64_u32 v[2:3], s[12:13], v0, s55, v[10:11]
	ds_read_b128 v[2:5], v2
	v_add_u32_e32 v6, s41, v0
	v_ashrrev_i32_e32 v7, 31, v6
	v_add_u32_e32 v0, 0xd00, v189
	v_lshlrev_b64 v[6:7], 11, v[6:7]
	v_ashrrev_i32_e32 v0, 5, v0
	v_lshl_add_u64 v[14:15], v[12:13], 0, v[6:7]
	v_mad_u64_u32 v[6:7], s[12:13], v0, s55, v[10:11]
	ds_read_b128 v[6:9], v6
	s_waitcnt lgkmcnt(1)
	global_store_dwordx4 v[14:15], v[2:5], off nt
	s_nop 1
	v_add_u32_e32 v2, s41, v0
	v_ashrrev_i32_e32 v3, 31, v2
	v_lshlrev_b64 v[2:3], 11, v[2:3]
	v_add_u32_e32 v0, 0xe00, v189
	v_lshl_add_u64 v[2:3], v[12:13], 0, v[2:3]
	v_ashrrev_i32_e32 v0, 5, v0
	s_waitcnt lgkmcnt(0)
	global_store_dwordx4 v[2:3], v[6:9], off nt
	v_mad_u64_u32 v[2:3], s[12:13], v0, s55, v[10:11]
	ds_read_b128 v[2:5], v2
	v_add_u32_e32 v6, s41, v0
	v_ashrrev_i32_e32 v7, 31, v6
	v_add_u32_e32 v0, 0xf00, v189
	v_lshlrev_b64 v[6:7], 11, v[6:7]
	v_ashrrev_i32_e32 v0, 5, v0
	v_lshl_add_u64 v[14:15], v[12:13], 0, v[6:7]
	v_mad_u64_u32 v[6:7], s[12:13], v0, s55, v[10:11]
	ds_read_b128 v[6:9], v6
	s_waitcnt lgkmcnt(1)
	global_store_dwordx4 v[14:15], v[2:5], off nt
	s_mov_b64 s[12:13], 0
	s_nop 0
	v_add_u32_e32 v2, s41, v0
	v_ashrrev_i32_e32 v3, 31, v2
	v_lshlrev_b64 v[2:3], 11, v[2:3]
	v_lshl_add_u64 v[2:3], v[12:13], 0, v[2:3]
	s_waitcnt lgkmcnt(0)
	global_store_dwordx4 v[2:3], v[6:9], off nt
	s_barrier

; #define LAS __attribute__((address_space(3)))
; DI f32x16 mfma32(bf16x8 a, bf16x8 b, f32x16 c) { return __builtin_amdgcn_mfma_f32_32x32x16_bf16(a, b, c, 0, 0, 0); }
;     ...
;   for (int kt = 0; kt < nk; ++kt) {
;     const int kn = (kt + 2 < nk) ? (kt + 2) : (nk - 1);
;     const LAS char* cur = lds + s0;
;     bf16x8 af[2][2], bfr[2][4];
; #pragma unroll
;     for (int kk = 0; kk < 2; ++kk) {
;       const int xo = kk ? x1 : x0;
;       af[kk][0] = *(const LAS bf16x8*)(cur + a_rd + xo);
;       bfr[kk][0] = *(const LAS bf16x8*)(cur + b_rd + xo);
;       bfr[kk][1] = *(const LAS bf16x8*)(cur + b_rd + 2048 + xo);
;       af[kk][1] = *(const LAS bf16x8*)(cur + a_rd + 2048 + xo);
;       bfr[kk][2] = *(const LAS bf16x8*)(cur + b_rd + 4096 + xo);
;       bfr[kk][3] = *(const LAS bf16x8*)(cur + b_rd + 6144 + xo);
;     }
;     DMA_STEP_(kn, s2);
; #pragma unroll
;     for (int kk = 0; kk < 2; ++kk) {
;       acc[0][0] = mfma32(bfr[kk][0], af[kk][0], acc[0][0]); acc[0][1] = mfma32(bfr[kk][1], af[kk][0], acc[0][1]);
;       acc[1][0] = mfma32(bfr[kk][0], af[kk][1], acc[1][0]); acc[1][1] = mfma32(bfr[kk][1], af[kk][1], acc[1][1]);
;       acc[0][2] = mfma32(bfr[kk][2], af[kk][0], acc[0][2]); acc[0][3] = mfma32(bfr[kk][3], af[kk][0], acc[0][3]);
;       acc[1][2] = mfma32(bfr[kk][2], af[kk][1], acc[1][2]); acc[1][3] = mfma32(bfr[kk][3], af[kk][1], acc[1][3]);
;     }
;     __builtin_amdgcn_sched_group_barrier(0x100, 12, 0);
;     __builtin_amdgcn_sched_group_barrier(0x010, 6, 0);
;     __builtin_amdgcn_sched_group_barrier(0x008, 16, 0);
;     asm volatile("s_waitcnt vmcnt(6) lgkmcnt(0)" ::: "memory");
;     __builtin_amdgcn_s_barrier();
;     asm volatile("" ::: "memory");
;     s0 = (s0 == 2 * STG) ? 0 : s0 + STG;
;     s2 = (s2 == 2 * STG) ? 0 : s2 + STG;
;   }
.LBB0_152:
	ds_read_b128 v[138:141], v228 offset:0
	ds_read_b128 v[166:169], v229 offset:8192
	ds_read_b128 v[154:157], v229 offset:10240
	ds_read_b128 v[142:145], v228 offset:2048
	ds_read_b128 v[146:149], v229 offset:12288
	ds_read_b128 v[150:153], v229 offset:14336
	s_add_i32 m0, s45, 0xc000
	s_waitcnt lgkmcnt(6)
	v_mfma_f32_32x32x16_bf16 v[114:129], v[182:185], v[158:161], v[114:129]
	global_load_lds_dwordx4 v238, vcc
	s_add_i32 m0, s45, 0xc400
	s_add_u32 vcc_lo, vcc_lo, 64
	s_addc_u32 vcc_hi, vcc_hi, 0
	v_mfma_f32_32x32x16_bf16 v[98:113], v[178:181], v[158:161], v[98:113]
	global_load_lds_dwordx4 v238, s[70:71]
	s_add_i32 m0, s44, 0xe000
	s_add_u32 s70, s70, 64
	s_addc_u32 s71, s71, 0
	v_mfma_f32_32x32x16_bf16 v[66:81], v[182:185], v[162:165], v[66:81]
	global_load_lds_dwordx4 v239, s[100:101]
	v_mfma_f32_32x32x16_bf16 v[34:49], v[178:181], v[162:165], v[34:49]
	global_load_lds_dwordx4 v239, s[100:101] offset:1024
	v_mfma_f32_32x32x16_bf16 v[82:97], v[174:177], v[158:161], v[82:97]
	global_load_lds_dwordx4 v239, s[100:101] offset:2048
	v_mfma_f32_32x32x16_bf16 v[50:65], v[170:173], v[158:161], v[50:65]
	global_load_lds_dwordx4 v239, s[100:101] offset:3072
	s_add_u32 s100, s100, 0xc000
	s_addc_u32 s101, s101, 0
	v_mfma_f32_32x32x16_bf16 v[18:33], v[174:177], v[162:165], v[18:33]
	v_mfma_f32_32x32x16_bf16 v[2:17], v[170:173], v[162:165], v[2:17]
	s_waitcnt vmcnt(6) lgkmcnt(0)
	s_barrier
	ds_read_b128 v[158:161], v226 offset:24576
	ds_read_b128 v[182:185], v227 offset:32768
	ds_read_b128 v[178:181], v227 offset:34816
	ds_read_b128 v[162:165], v226 offset:26624
	ds_read_b128 v[174:177], v227 offset:36864
	ds_read_b128 v[170:173], v227 offset:38912
	v_mfma_f32_32x32x16_bf16 v[114:129], v[166:169], v[138:141], v[114:129]
	v_mfma_f32_32x32x16_bf16 v[98:113], v[154:157], v[138:141], v[98:113]
	v_mfma_f32_32x32x16_bf16 v[66:81], v[166:169], v[142:145], v[66:81]
	v_mfma_f32_32x32x16_bf16 v[34:49], v[154:157], v[142:145], v[34:49]
	v_mfma_f32_32x32x16_bf16 v[82:97], v[146:149], v[138:141], v[82:97]
	v_mfma_f32_32x32x16_bf16 v[50:65], v[150:153], v[138:141], v[50:65]
	v_mfma_f32_32x32x16_bf16 v[18:33], v[146:149], v[142:145], v[18:33]
	v_mfma_f32_32x32x16_bf16 v[2:17], v[150:153], v[142:145], v[2:17]
	ds_read_b128 v[138:141], v228 offset:24576
	ds_read_b128 v[166:169], v229 offset:32768
	ds_read_b128 v[154:157], v229 offset:34816
	ds_read_b128 v[142:145], v228 offset:26624
	ds_read_b128 v[146:149], v229 offset:36864
	ds_read_b128 v[150:153], v229 offset:38912
	s_add_i32 m0, s45, 0x0
	s_waitcnt lgkmcnt(6)
	v_mfma_f32_32x32x16_bf16 v[114:129], v[182:185], v[158:161], v[114:129]
	global_load_lds_dwordx4 v238, vcc
	s_add_i32 m0, s45, 0x400
	s_add_u32 vcc_lo, vcc_lo, 64
	s_addc_u32 vcc_hi, vcc_hi, 0
	v_mfma_f32_32x32x16_bf16 v[98:113], v[178:181], v[158:161], v[98:113]
	global_load_lds_dwordx4 v238, s[70:71]
	s_add_i32 m0, s44, 0x2000
	s_add_u32 s70, s70, 64
	s_addc_u32 s71, s71, 0
	v_mfma_f32_32x32x16_bf16 v[66:81], v[182:185], v[162:165], v[66:81]
	global_load_lds_dwordx4 v239, s[100:101]
	v_mfma_f32_32x32x16_bf16 v[34:49], v[178:181], v[162:165], v[34:49]
	global_load_lds_dwordx4 v239, s[100:101] offset:1024
	v_mfma_f32_32x32x16_bf16 v[82:97], v[174:177], v[158:161], v[82:97]
	global_load_lds_dwordx4 v239, s[100:101] offset:2048
	v_mfma_f32_32x32x16_bf16 v[50:65], v[170:173], v[158:161], v[50:65]
	global_load_lds_dwordx4 v239, s[100:101] offset:3072
	s_add_u32 s100, s100, 0xc000
	s_addc_u32 s101, s101, 0
	v_mfma_f32_32x32x16_bf16 v[18:33], v[174:177], v[162:165], v[18:33]
	v_mfma_f32_32x32x16_bf16 v[2:17], v[170:173], v[162:165], v[2:17]
	s_waitcnt vmcnt(6) lgkmcnt(0)
	s_barrier
	ds_read_b128 v[158:161], v226 offset:49152
	ds_read_b128 v[182:185], v227 offset:57344
	ds_read_b128 v[178:181], v227 offset:59392
	ds_read_b128 v[162:165], v226 offset:51200
	ds_read_b128 v[174:177], v227 offset:61440
	ds_read_b128 v[170:173], v227 offset:63488
	v_mfma_f32_32x32x16_bf16 v[114:129], v[166:169], v[138:141], v[114:129]
	v_mfma_f32_32x32x16_bf16 v[98:113], v[154:157], v[138:141], v[98:113]
	v_mfma_f32_32x32x16_bf16 v[66:81], v[166:169], v[142:145], v[66:81]
	v_mfma_f32_32x32x16_bf16 v[34:49], v[154:157], v[142:145], v[34:49]
	v_mfma_f32_32x32x16_bf16 v[82:97], v[146:149], v[138:141], v[82:97]
	v_mfma_f32_32x32x16_bf16 v[50:65], v[150:153], v[138:141], v[50:65]
	v_mfma_f32_32x32x16_bf16 v[18:33], v[146:149], v[142:145], v[18:33]
	v_mfma_f32_32x32x16_bf16 v[2:17], v[150:153], v[142:145], v[2:17]
	ds_read_b128 v[138:141], v228 offset:49152
	ds_read_b128 v[166:169], v229 offset:57344
	ds_read_b128 v[154:157], v229 offset:59392
	ds_read_b128 v[142:145], v228 offset:51200
	ds_read_b128 v[146:149], v229 offset:61440
	ds_read_b128 v[150:153], v229 offset:63488
	s_add_i32 m0, s45, 0x6000
	s_waitcnt lgkmcnt(6)
	v_mfma_f32_32x32x16_bf16 v[114:129], v[182:185], v[158:161], v[114:129]
	global_load_lds_dwordx4 v238, vcc
	s_add_i32 m0, s45, 0x6400
	s_add_u32 vcc_lo, vcc_lo, 64
	s_addc_u32 vcc_hi, vcc_hi, 0
	v_mfma_f32_32x32x16_bf16 v[98:113], v[178:181], v[158:161], v[98:113]
	global_load_lds_dwordx4 v238, s[70:71]
	s_add_i32 m0, s44, 0x8000
	s_add_u32 s70, s70, 64
	s_addc_u32 s71, s71, 0
	v_mfma_f32_32x32x16_bf16 v[66:81], v[182:185], v[162:165], v[66:81]
	global_load_lds_dwordx4 v239, s[100:101]
	v_mfma_f32_32x32x16_bf16 v[34:49], v[178:181], v[162:165], v[34:49]
	global_load_lds_dwordx4 v239, s[100:101] offset:1024
	v_mfma_f32_32x32x16_bf16 v[82:97], v[174:177], v[158:161], v[82:97]
	global_load_lds_dwordx4 v239, s[100:101] offset:2048
	v_mfma_f32_32x32x16_bf16 v[50:65], v[170:173], v[158:161], v[50:65]
	global_load_lds_dwordx4 v239, s[100:101] offset:3072
	s_add_u32 s100, s100, 0xc000
	s_addc_u32 s101, s101, 0
	v_mfma_f32_32x32x16_bf16 v[18:33], v[174:177], v[162:165], v[18:33]
	v_mfma_f32_32x32x16_bf16 v[2:17], v[170:173], v[162:165], v[2:17]
	s_waitcnt vmcnt(6) lgkmcnt(0)
	s_barrier
; #define LAS __attribute__((address_space(3)))
; DI unsigned pk2(float a, float b) { f32x2 v = {a, b}; bf2_t r = __builtin_convertvector(v, bf2_t); return __builtin_bit_cast(unsigned, r); }
;     ...
;   for (int kt = 0; kt < nk; ++kt) {
;     const int kn = (kt + 2 < nk) ? (kt + 2) : (nk - 1);
;     const LAS char* cur = lds + s0;
;     bf16x8 af[2][2], bfr[2][4];
; #pragma unroll
;     for (int kk = 0; kk < 2; ++kk) {
;       const int xo = kk ? x1 : x0;
;       af[kk][0] = *(const LAS bf16x8*)(cur + a_rd + xo);
;       bfr[kk][0] = *(const LAS bf16x8*)(cur + b_rd + xo);
;       bfr[kk][1] = *(const LAS bf16x8*)(cur + b_rd + 2048 + xo);
;       af[kk][1] = *(const LAS bf16x8*)(cur + a_rd + 2048 + xo);
;       bfr[kk][2] = *(const LAS bf16x8*)(cur + b_rd + 4096 + xo);
;       bfr[kk][3] = *(const LAS bf16x8*)(cur + b_rd + 6144 + xo);
;     }
;     DMA_STEP_(kn, s2);
; #pragma unroll
;     for (int kk = 0; kk < 2; ++kk) {
;       acc[0][0] = mfma32(bfr[kk][0], af[kk][0], acc[0][0]); acc[0][1] = mfma32(bfr[kk][1], af[kk][0], acc[0][1]);
;       acc[1][0] = mfma32(bfr[kk][0], af[kk][1], acc[1][0]); acc[1][1] = mfma32(bfr[kk][1], af[kk][1], acc[1][1]);
;       acc[0][2] = mfma32(bfr[kk][2], af[kk][0], acc[0][2]); acc[0][3] = mfma32(bfr[kk][3], af[kk][0], acc[0][3]);
;       acc[1][2] = mfma32(bfr[kk][2], af[kk][1], acc[1][2]); acc[1][3] = mfma32(bfr[kk][3], af[kk][1], acc[1][3]);
;     }
;     __builtin_amdgcn_sched_group_barrier(0x100, 12, 0);
;     __builtin_amdgcn_sched_group_barrier(0x010, 6, 0);
;     __builtin_amdgcn_sched_group_barrier(0x008, 16, 0);
;     asm volatile("s_waitcnt vmcnt(6) lgkmcnt(0)" ::: "memory");
;     __builtin_amdgcn_s_barrier();
;     asm volatile("" ::: "memory");
;     s0 = (s0 == 2 * STG) ? 0 : s0 + STG;
;     s2 = (s2 == 2 * STG) ? 0 : s2 + STG;
;   }
;   asm volatile("s_waitcnt vmcnt(0)" ::: "memory");
;   __builtin_amdgcn_s_barrier();
;   asm volatile("" ::: "memory");
;     ...
;   {
;     const int h = lane >> 5, cl = lane & 31;
; #pragma unroll
;     for (int i = 0; i < 2; ++i)
; #pragma unroll
;       for (int j = 0; j < 4; ++j)
; #pragma unroll
;         for (int g = 0; g < 4; ++g) {
;           u32x2 w; w.x = pk2(acc[i][j][4 * g], acc[i][j][4 * g + 1]); w.y = pk2(acc[i][j][4 * g + 2], acc[i][j][4 * g + 3]);
;           *(u32x2*)(smem + (wr * 64 + i * 32 + cl) * 528 + (wc * 128 + j * 32 + 8 * g + 4 * h) * 2) = w;
	ds_read_b128 v[158:161], v226 offset:0
	ds_read_b128 v[182:185], v227 offset:8192
	ds_read_b128 v[178:181], v227 offset:10240
	ds_read_b128 v[162:165], v226 offset:2048
	ds_read_b128 v[174:177], v227 offset:12288
	ds_read_b128 v[170:173], v227 offset:14336
	v_mfma_f32_32x32x16_bf16 v[114:129], v[166:169], v[138:141], v[114:129]
	v_mfma_f32_32x32x16_bf16 v[98:113], v[154:157], v[138:141], v[98:113]
	v_mfma_f32_32x32x16_bf16 v[66:81], v[166:169], v[142:145], v[66:81]
	v_mfma_f32_32x32x16_bf16 v[34:49], v[154:157], v[142:145], v[34:49]
	v_mfma_f32_32x32x16_bf16 v[82:97], v[146:149], v[138:141], v[82:97]
	v_mfma_f32_32x32x16_bf16 v[50:65], v[150:153], v[138:141], v[50:65]
	v_mfma_f32_32x32x16_bf16 v[18:33], v[146:149], v[142:145], v[18:33]
	v_mfma_f32_32x32x16_bf16 v[2:17], v[150:153], v[142:145], v[2:17]
	ds_read_b128 v[138:141], v228 offset:0
	ds_read_b128 v[166:169], v229 offset:8192
	ds_read_b128 v[154:157], v229 offset:10240
	ds_read_b128 v[142:145], v228 offset:2048
	ds_read_b128 v[146:149], v229 offset:12288
	ds_read_b128 v[150:153], v229 offset:14336
	s_add_i32 m0, s45, 0xc000
	s_waitcnt lgkmcnt(6)
	v_mfma_f32_32x32x16_bf16 v[114:129], v[182:185], v[158:161], v[114:129]
	global_load_lds_dwordx4 v238, vcc
	s_add_i32 m0, s45, 0xc400
	s_add_u32 vcc_lo, vcc_lo, 64
	s_addc_u32 vcc_hi, vcc_hi, 0
	v_mfma_f32_32x32x16_bf16 v[98:113], v[178:181], v[158:161], v[98:113]
	global_load_lds_dwordx4 v238, s[70:71]
	s_add_i32 m0, s44, 0xe000
	s_add_u32 s70, s70, 64
	s_addc_u32 s71, s71, 0
	v_mfma_f32_32x32x16_bf16 v[66:81], v[182:185], v[162:165], v[66:81]
	global_load_lds_dwordx4 v239, s[100:101]
	v_mfma_f32_32x32x16_bf16 v[34:49], v[178:181], v[162:165], v[34:49]
	global_load_lds_dwordx4 v239, s[100:101] offset:1024
	v_mfma_f32_32x32x16_bf16 v[82:97], v[174:177], v[158:161], v[82:97]
	global_load_lds_dwordx4 v239, s[100:101] offset:2048
	v_mfma_f32_32x32x16_bf16 v[50:65], v[170:173], v[158:161], v[50:65]
	global_load_lds_dwordx4 v239, s[100:101] offset:3072
	s_add_u32 s100, s100, 0xc000
	s_addc_u32 s101, s101, 0
	v_mfma_f32_32x32x16_bf16 v[18:33], v[174:177], v[162:165], v[18:33]
	v_mfma_f32_32x32x16_bf16 v[2:17], v[170:173], v[162:165], v[2:17]
	s_waitcnt vmcnt(6) lgkmcnt(0)
	s_barrier
	ds_read_b128 v[158:161], v226 offset:24576
	ds_read_b128 v[182:185], v227 offset:32768
	ds_read_b128 v[178:181], v227 offset:34816
	ds_read_b128 v[162:165], v226 offset:26624
	ds_read_b128 v[174:177], v227 offset:36864
	ds_read_b128 v[170:173], v227 offset:38912
	v_mfma_f32_32x32x16_bf16 v[114:129], v[166:169], v[138:141], v[114:129]
	v_mfma_f32_32x32x16_bf16 v[98:113], v[154:157], v[138:141], v[98:113]
	v_mfma_f32_32x32x16_bf16 v[66:81], v[166:169], v[142:145], v[66:81]
	v_mfma_f32_32x32x16_bf16 v[34:49], v[154:157], v[142:145], v[34:49]
	v_mfma_f32_32x32x16_bf16 v[82:97], v[146:149], v[138:141], v[82:97]
	v_mfma_f32_32x32x16_bf16 v[50:65], v[150:153], v[138:141], v[50:65]
	v_mfma_f32_32x32x16_bf16 v[18:33], v[146:149], v[142:145], v[18:33]
	v_mfma_f32_32x32x16_bf16 v[2:17], v[150:153], v[142:145], v[2:17]
	ds_read_b128 v[138:141], v228 offset:24576
	ds_read_b128 v[166:169], v229 offset:32768
	ds_read_b128 v[154:157], v229 offset:34816
	ds_read_b128 v[142:145], v228 offset:26624
	ds_read_b128 v[146:149], v229 offset:36864
	ds_read_b128 v[150:153], v229 offset:38912
	s_waitcnt lgkmcnt(6)
	v_mfma_f32_32x32x16_bf16 v[114:129], v[182:185], v[158:161], v[114:129]
	v_mfma_f32_32x32x16_bf16 v[98:113], v[178:181], v[158:161], v[98:113]
	v_mfma_f32_32x32x16_bf16 v[66:81], v[182:185], v[162:165], v[66:81]
	v_mfma_f32_32x32x16_bf16 v[34:49], v[178:181], v[162:165], v[34:49]
	v_mfma_f32_32x32x16_bf16 v[82:97], v[174:177], v[158:161], v[82:97]
	v_mfma_f32_32x32x16_bf16 v[50:65], v[170:173], v[158:161], v[50:65]
	v_mfma_f32_32x32x16_bf16 v[18:33], v[174:177], v[162:165], v[18:33]
	v_mfma_f32_32x32x16_bf16 v[2:17], v[170:173], v[162:165], v[2:17]
	s_waitcnt vmcnt(0) lgkmcnt(0)
	s_barrier
	ds_read_b128 v[158:161], v226 offset:49152
	ds_read_b128 v[182:185], v227 offset:57344
	ds_read_b128 v[178:181], v227 offset:59392
	ds_read_b128 v[162:165], v226 offset:51200
	ds_read_b128 v[174:177], v227 offset:61440
	ds_read_b128 v[170:173], v227 offset:63488
	v_mfma_f32_32x32x16_bf16 v[114:129], v[166:169], v[138:141], v[114:129]
	v_mfma_f32_32x32x16_bf16 v[98:113], v[154:157], v[138:141], v[98:113]
	v_mfma_f32_32x32x16_bf16 v[66:81], v[166:169], v[142:145], v[66:81]
	v_mfma_f32_32x32x16_bf16 v[34:49], v[154:157], v[142:145], v[34:49]
	v_mfma_f32_32x32x16_bf16 v[82:97], v[146:149], v[138:141], v[82:97]
	v_mfma_f32_32x32x16_bf16 v[50:65], v[150:153], v[138:141], v[50:65]
	v_mfma_f32_32x32x16_bf16 v[18:33], v[146:149], v[142:145], v[18:33]
	v_mfma_f32_32x32x16_bf16 v[2:17], v[150:153], v[142:145], v[2:17]
	ds_read_b128 v[138:141], v228 offset:49152
	ds_read_b128 v[166:169], v229 offset:57344
	ds_read_b128 v[154:157], v229 offset:59392
	ds_read_b128 v[142:145], v228 offset:51200
	ds_read_b128 v[146:149], v229 offset:61440
	ds_read_b128 v[150:153], v229 offset:63488
	s_waitcnt lgkmcnt(6)
	v_mfma_f32_32x32x16_bf16 v[114:129], v[182:185], v[158:161], v[114:129]
	v_mfma_f32_32x32x16_bf16 v[98:113], v[178:181], v[158:161], v[98:113]
	v_mfma_f32_32x32x16_bf16 v[66:81], v[182:185], v[162:165], v[66:81]
	v_mfma_f32_32x32x16_bf16 v[34:49], v[178:181], v[162:165], v[34:49]
	v_mfma_f32_32x32x16_bf16 v[82:97], v[174:177], v[158:161], v[82:97]
	v_mfma_f32_32x32x16_bf16 v[50:65], v[170:173], v[158:161], v[50:65]
	v_mfma_f32_32x32x16_bf16 v[18:33], v[174:177], v[162:165], v[18:33]
	v_mfma_f32_32x32x16_bf16 v[2:17], v[170:173], v[162:165], v[2:17]
	s_waitcnt lgkmcnt(0)
	v_mfma_f32_32x32x16_bf16 v[114:129], v[166:169], v[138:141], v[114:129]
	v_mfma_f32_32x32x16_bf16 v[98:113], v[154:157], v[138:141], v[98:113]
	v_mfma_f32_32x32x16_bf16 v[66:81], v[166:169], v[142:145], v[66:81]
	v_mfma_f32_32x32x16_bf16 v[34:49], v[154:157], v[142:145], v[34:49]
	v_mfma_f32_32x32x16_bf16 v[82:97], v[146:149], v[138:141], v[82:97]
	v_mfma_f32_32x32x16_bf16 v[50:65], v[150:153], v[138:141], v[50:65]
	v_mfma_f32_32x32x16_bf16 v[18:33], v[146:149], v[142:145], v[18:33]
	v_mfma_f32_32x32x16_bf16 v[2:17], v[150:153], v[142:145], v[2:17]
	s_waitcnt lgkmcnt(0)
	s_mov_b32 s101, 0
	s_mov_b32 s71, 0
	s_setprio 0
	v_mul_lo_u32 v0, v197, s55
	v_add_u32_e32 v0, 16, v0
	s_nop 1
	v_cvt_pk_bf16_f32 v114, v114, v115
	v_cvt_pk_bf16_f32 v115, v116, v117
	v_lshlrev_b32_e32 v116, 3, v196
	s_lshl_b32 s10, s43, 1
	v_add3_u32 v0, v0, v116, s10
	v_cvt_pk_bf16_f32 v116, v118, v119
	v_cvt_pk_bf16_f32 v117, v120, v121
	v_cvt_pk_bf16_f32 v98, v98, v99
	v_cvt_pk_bf16_f32 v99, v100, v101
	v_cvt_pk_bf16_f32 v100, v102, v103
	v_cvt_pk_bf16_f32 v101, v104, v105
	v_cvt_pk_bf16_f32 v82, v82, v83
	v_cvt_pk_bf16_f32 v83, v84, v85
	v_cvt_pk_bf16_f32 v84, v86, v87
	v_cvt_pk_bf16_f32 v85, v88, v89
	v_cvt_pk_bf16_f32 v50, v50, v51
	v_cvt_pk_bf16_f32 v51, v52, v53
	v_cvt_pk_bf16_f32 v52, v54, v55
	v_cvt_pk_bf16_f32 v53, v56, v57
	s_waitcnt vmcnt(0)
	s_barrier
; DI unsigned pk2(float a, float b) { f32x2 v = {a, b}; bf2_t r = __builtin_convertvector(v, bf2_t); return __builtin_bit_cast(unsigned, r); }
;     ...
;   {
;     const int h = lane >> 5, cl = lane & 31;
; #pragma unroll
;     for (int i = 0; i < 2; ++i)
; #pragma unroll
;       for (int j = 0; j < 4; ++j)
; #pragma unroll
;         for (int g = 0; g < 4; ++g) {
;           u32x2 w; w.x = pk2(acc[i][j][4 * g], acc[i][j][4 * g + 1]); w.y = pk2(acc[i][j][4 * g + 2], acc[i][j][4 * g + 3]);
;           *(u32x2*)(smem + (wr * 64 + i * 32 + cl) * 528 + (wc * 128 + j * 32 + 8 * g + 4 * h) * 2) = w;
;         }
;   }
;   __syncthreads();
	ds_write2_b64 v0, v[114:115], v[116:117] offset1:2
	v_cvt_pk_bf16_f32 v114, v122, v123
	v_cvt_pk_bf16_f32 v115, v124, v125
	v_cvt_pk_bf16_f32 v116, v126, v127
	v_cvt_pk_bf16_f32 v117, v128, v129
	ds_write2_b64 v0, v[98:99], v[100:101] offset0:8 offset1:10
	v_cvt_pk_bf16_f32 v98, v106, v107
	v_cvt_pk_bf16_f32 v99, v108, v109
	v_cvt_pk_bf16_f32 v100, v110, v111
	v_cvt_pk_bf16_f32 v101, v112, v113
	ds_write2_b64 v0, v[82:83], v[84:85] offset0:16 offset1:18
	v_cvt_pk_bf16_f32 v82, v90, v91
	v_cvt_pk_bf16_f32 v83, v92, v93
	v_cvt_pk_bf16_f32 v84, v94, v95
	v_cvt_pk_bf16_f32 v85, v96, v97
	ds_write2_b64 v0, v[50:51], v[52:53] offset0:24 offset1:26
	v_cvt_pk_bf16_f32 v50, v58, v59
	v_cvt_pk_bf16_f32 v51, v60, v61
	v_cvt_pk_bf16_f32 v52, v62, v63
	v_cvt_pk_bf16_f32 v53, v64, v65
	ds_write2_b64 v0, v[114:115], v[116:117] offset0:4 offset1:6
	ds_write2_b64 v0, v[98:99], v[100:101] offset0:12 offset1:14
	ds_write2_b64 v0, v[82:83], v[84:85] offset0:20 offset1:22
	ds_write2_b64 v0, v[50:51], v[52:53] offset0:28 offset1:30
	v_cvt_pk_bf16_f32 v50, v66, v67
	v_cvt_pk_bf16_f32 v51, v68, v69
	v_cvt_pk_bf16_f32 v52, v70, v71
	v_cvt_pk_bf16_f32 v53, v72, v73
	v_add_u32_e32 v0, 0x4000, v0
	v_cvt_pk_bf16_f32 v34, v34, v35
	v_cvt_pk_bf16_f32 v35, v36, v37
	v_cvt_pk_bf16_f32 v36, v38, v39
	v_cvt_pk_bf16_f32 v37, v40, v41
	v_cvt_pk_bf16_f32 v18, v18, v19
	v_cvt_pk_bf16_f32 v19, v20, v21
	v_cvt_pk_bf16_f32 v20, v22, v23
	v_cvt_pk_bf16_f32 v21, v24, v25
	v_cvt_pk_bf16_f32 v2, v2, v3
	v_cvt_pk_bf16_f32 v3, v4, v5
	v_cvt_pk_bf16_f32 v4, v6, v7
	v_cvt_pk_bf16_f32 v5, v8, v9
	ds_write2_b64 v0, v[50:51], v[52:53] offset0:64 offset1:66
	v_cvt_pk_bf16_f32 v50, v74, v75
	v_cvt_pk_bf16_f32 v51, v76, v77
	v_cvt_pk_bf16_f32 v52, v78, v79
	v_cvt_pk_bf16_f32 v53, v80, v81
	ds_write2_b64 v0, v[34:35], v[36:37] offset0:72 offset1:74
	v_cvt_pk_bf16_f32 v34, v42, v43
	v_cvt_pk_bf16_f32 v35, v44, v45
	v_cvt_pk_bf16_f32 v36, v46, v47
	v_cvt_pk_bf16_f32 v37, v48, v49
	ds_write2_b64 v0, v[18:19], v[20:21] offset0:80 offset1:82
	v_cvt_pk_bf16_f32 v18, v26, v27
	v_cvt_pk_bf16_f32 v19, v28, v29
	v_cvt_pk_bf16_f32 v20, v30, v31
	v_cvt_pk_bf16_f32 v21, v32, v33
	ds_write2_b64 v0, v[2:3], v[4:5] offset0:88 offset1:90
	v_cvt_pk_bf16_f32 v2, v10, v11
	v_cvt_pk_bf16_f32 v3, v12, v13
	v_cvt_pk_bf16_f32 v4, v14, v15
	v_cvt_pk_bf16_f32 v5, v16, v17
	s_lshl_b64 s[12:13], s[12:13], 1
	ds_write2_b64 v0, v[50:51], v[52:53] offset0:68 offset1:70
	ds_write2_b64 v0, v[34:35], v[36:37] offset0:76 offset1:78
	ds_write2_b64 v0, v[18:19], v[20:21] offset0:84 offset1:86
	ds_write2_b64 v0, v[2:3], v[4:5] offset0:92 offset1:94
	s_waitcnt vmcnt(0) lgkmcnt(0)
	s_barrier
; #define GAS __attribute__((address_space(1)))
;     ...
;   int tid2 = tid; asm volatile("" : "+v"(tid2));
;   if (EPI == 0) {
; #pragma unroll
;     for (int i = 0; i < 16; ++i) {
;       const int id = tid2 + 256 * i, r = id >> 5, c8 = (id & 31) * 8;
;       const u32x4 v = *(const u32x4*)(smem + r * 528 + c8 * 2);
;       *(GAS u32x4*)(ea.out + (size_t)(m0 + r) * ea.ldo + n0 + c8) = v;
;     }
	s_add_u32 s12, s14, s12
	v_lshlrev_b32_e32 v0, 4, v189
	v_and_b32_e32 v0, 0x1f0, v0
	s_addc_u32 s13, s15, s13
	v_add_u32_e32 v10, 16, v0
	v_lshl_add_u64 v[12:13], s[12:13], 0, v[0:1]
	v_ashrrev_i32_e32 v0, 5, v189
	v_mad_u64_u32 v[2:3], s[12:13], v0, s55, v[10:11]
	v_add_u32_e32 v0, s41, v0
	s_movk_i32 s10, 0x600
	v_mad_i64_i32 v[14:15], s[12:13], v0, s10, v[12:13]
	v_add_u32_e32 v0, 0x100, v189
	ds_read_b128 v[2:5], v2
	v_ashrrev_i32_e32 v0, 5, v0
	v_mad_u64_u32 v[6:7], s[12:13], v0, s55, v[10:11]
	ds_read_b128 v[6:9], v6
	v_add_u32_e32 v0, s41, v0
	s_waitcnt lgkmcnt(1)
	global_store_dwordx4 v[14:15], v[2:5], off nt
	v_readlane_b32 s44, v250, 17
	s_nop 0
	v_mad_i64_i32 v[2:3], s[12:13], v0, s10, v[12:13]
	v_add_u32_e32 v0, 0x200, v189
	v_ashrrev_i32_e32 v0, 5, v0
	s_waitcnt lgkmcnt(0)
	global_store_dwordx4 v[2:3], v[6:9], off nt
	v_mad_u64_u32 v[2:3], s[12:13], v0, s55, v[10:11]
	v_add_u32_e32 v0, s41, v0
	v_mad_i64_i32 v[14:15], s[12:13], v0, s10, v[12:13]
	v_add_u32_e32 v0, 0x300, v189
	ds_read_b128 v[2:5], v2
	v_ashrrev_i32_e32 v0, 5, v0
	v_mad_u64_u32 v[6:7], s[12:13], v0, s55, v[10:11]
	ds_read_b128 v[6:9], v6
	v_add_u32_e32 v0, s41, v0
	s_waitcnt lgkmcnt(1)
	global_store_dwordx4 v[14:15], v[2:5], off nt
	s_nop 1
	v_mad_i64_i32 v[2:3], s[12:13], v0, s10, v[12:13]
	v_add_u32_e32 v0, 0x400, v189
	v_ashrrev_i32_e32 v0, 5, v0
	s_waitcnt lgkmcnt(0)
	global_store_dwordx4 v[2:3], v[6:9], off nt
	v_mad_u64_u32 v[2:3], s[12:13], v0, s55, v[10:11]
	v_add_u32_e32 v0, s41, v0
	v_mad_i64_i32 v[14:15], s[12:13], v0, s10, v[12:13]
	v_add_u32_e32 v0, 0x500, v189
	ds_read_b128 v[2:5], v2
	v_ashrrev_i32_e32 v0, 5, v0
	v_mad_u64_u32 v[6:7], s[12:13], v0, s55, v[10:11]
	ds_read_b128 v[6:9], v6
	v_add_u32_e32 v0, s41, v0
	s_waitcnt lgkmcnt(1)
	global_store_dwordx4 v[14:15], v[2:5], off nt
	s_nop 1
	v_mad_i64_i32 v[2:3], s[12:13], v0, s10, v[12:13]
	v_add_u32_e32 v0, 0x600, v189
	v_ashrrev_i32_e32 v0, 5, v0
	s_waitcnt lgkmcnt(0)
	global_store_dwordx4 v[2:3], v[6:9], off nt
	v_mad_u64_u32 v[2:3], s[12:13], v0, s55, v[10:11]
	v_add_u32_e32 v0, s41, v0
	v_mad_i64_i32 v[14:15], s[12:13], v0, s10, v[12:13]
	v_add_u32_e32 v0, 0x700, v189
	ds_read_b128 v[2:5], v2
	v_ashrrev_i32_e32 v0, 5, v0
	v_mad_u64_u32 v[6:7], s[12:13], v0, s55, v[10:11]
	ds_read_b128 v[6:9], v6
	v_add_u32_e32 v0, s41, v0
	s_waitcnt lgkmcnt(1)
	global_store_dwordx4 v[14:15], v[2:5], off nt
	s_nop 1
	v_mad_i64_i32 v[2:3], s[12:13], v0, s10, v[12:13]
	v_add_u32_e32 v0, 0x800, v189
	v_ashrrev_i32_e32 v0, 5, v0
	s_waitcnt lgkmcnt(0)
	global_store_dwordx4 v[2:3], v[6:9], off nt
	v_mad_u64_u32 v[2:3], s[12:13], v0, s55, v[10:11]
	v_add_u32_e32 v0, s41, v0
	v_mad_i64_i32 v[14:15], s[12:13], v0, s10, v[12:13]
	v_add_u32_e32 v0, 0x900, v189
	ds_read_b128 v[2:5], v2
	v_ashrrev_i32_e32 v0, 5, v0
	v_mad_u64_u32 v[6:7], s[12:13], v0, s55, v[10:11]
	ds_read_b128 v[6:9], v6
	v_add_u32_e32 v0, s41, v0
	s_waitcnt lgkmcnt(1)
	global_store_dwordx4 v[14:15], v[2:5], off nt
	s_nop 1
	v_mad_i64_i32 v[2:3], s[12:13], v0, s10, v[12:13]
	v_add_u32_e32 v0, 0xa00, v189
	v_ashrrev_i32_e32 v0, 5, v0
	s_waitcnt lgkmcnt(0)
	global_store_dwordx4 v[2:3], v[6:9], off nt
	v_mad_u64_u32 v[2:3], s[12:13], v0, s55, v[10:11]
	v_add_u32_e32 v0, s41, v0
	v_mad_i64_i32 v[14:15], s[12:13], v0, s10, v[12:13]
	v_add_u32_e32 v0, 0xb00, v189
	ds_read_b128 v[2:5], v2
	v_ashrrev_i32_e32 v0, 5, v0
	v_mad_u64_u32 v[6:7], s[12:13], v0, s55, v[10:11]
	ds_read_b128 v[6:9], v6
	v_add_u32_e32 v0, s41, v0
	s_waitcnt lgkmcnt(1)
	global_store_dwordx4 v[14:15], v[2:5], off nt
	s_nop 1
	v_mad_i64_i32 v[2:3], s[12:13], v0, s10, v[12:13]
	v_add_u32_e32 v0, 0xc00, v189
	v_ashrrev_i32_e32 v0, 5, v0
	s_waitcnt lgkmcnt(0)
	global_store_dwordx4 v[2:3], v[6:9], off nt
	v_mad_u64_u32 v[2:3], s[12:13], v0, s55, v[10:11]
	v_add_u32_e32 v0, s41, v0
	v_mad_i64_i32 v[14:15], s[12:13], v0, s10, v[12:13]
	v_add_u32_e32 v0, 0xd00, v189
	ds_read_b128 v[2:5], v2
	v_ashrrev_i32_e32 v0, 5, v0
	v_mad_u64_u32 v[6:7], s[12:13], v0, s55, v[10:11]
	ds_read_b128 v[6:9], v6
	v_add_u32_e32 v0, s41, v0
	s_waitcnt lgkmcnt(1)
	global_store_dwordx4 v[14:15], v[2:5], off nt
	s_nop 1
	v_mad_i64_i32 v[2:3], s[12:13], v0, s10, v[12:13]
	v_add_u32_e32 v0, 0xe00, v189
	v_ashrrev_i32_e32 v0, 5, v0
	s_waitcnt lgkmcnt(0)
	global_store_dwordx4 v[2:3], v[6:9], off nt
	v_mad_u64_u32 v[2:3], s[12:13], v0, s55, v[10:11]
	v_add_u32_e32 v0, s41, v0
	v_mad_i64_i32 v[14:15], s[12:13], v0, s10, v[12:13]
	v_add_u32_e32 v0, 0xf00, v189
	v_ashrrev_i32_e32 v0, 5, v0
	ds_read_b128 v[2:5], v2
	v_mad_u64_u32 v[6:7], s[12:13], v0, s55, v[10:11]
	ds_read_b128 v[6:9], v6
	v_add_u32_e32 v0, s41, v0
	s_waitcnt lgkmcnt(1)
	global_store_dwordx4 v[14:15], v[2:5], off nt
	s_nop 1
	v_mad_i64_i32 v[2:3], s[12:13], v0, s10, v[12:13]
	s_waitcnt lgkmcnt(0)
	global_store_dwordx4 v[2:3], v[6:9], off nt
	s_barrier
	s_branch .LBB0_145
